# P2 epilogue: saddr-form stores; 6 of the 16 packed stores per wave deferred into the next unit's peeled first K-trip at one store per phase (3 still in their accumulator registers, 3 packed into freed
# speedup vs baseline: 1.0262x; 1.0076x over previous
.LBB0_214:
	s_load_dwordx2 s[60:61], s[62:63], 0xc0
	s_mul_i32 s18, s43, 49
	s_add_i32 s18, s18, s42
	s_ashr_i32 s19, s18, 31
	s_lshl_b64 s[18:19], s[18:19], 17
	v_cvt_pk_bf16_f32 v124, v124, v125
	v_cvt_pk_bf16_f32 v125, v126, v127
	v_cvt_pk_bf16_f32 v126, v128, v129
	v_cvt_pk_bf16_f32 v127, v130, v131
	v_cvt_pk_bf16_f32 v120, v120, v121
	v_cvt_pk_bf16_f32 v121, v122, v123
	v_cvt_pk_bf16_f32 v122, v116, v117
	v_cvt_pk_bf16_f32 v123, v118, v119
	v_cvt_pk_bf16_f32 v112, v112, v113
	v_cvt_pk_bf16_f32 v113, v114, v115
	v_cvt_pk_bf16_f32 v114, v108, v109
	v_cvt_pk_bf16_f32 v115, v110, v111
	v_cvt_pk_bf16_f32 v104, v104, v105
	v_cvt_pk_bf16_f32 v105, v106, v107
	v_cvt_pk_bf16_f32 v106, v100, v101
	v_cvt_pk_bf16_f32 v107, v102, v103
	v_cvt_pk_bf16_f32 v96, v96, v97
	v_cvt_pk_bf16_f32 v97, v98, v99
	v_cvt_pk_bf16_f32 v98, v92, v93
	v_cvt_pk_bf16_f32 v99, v94, v95
	v_cvt_pk_bf16_f32 v88, v88, v89
	v_cvt_pk_bf16_f32 v89, v90, v91
	v_cvt_pk_bf16_f32 v90, v84, v85
	v_cvt_pk_bf16_f32 v91, v86, v87
	v_cvt_pk_bf16_f32 v76, v76, v77
	v_cvt_pk_bf16_f32 v77, v78, v79
	v_cvt_pk_bf16_f32 v78, v72, v73
	v_cvt_pk_bf16_f32 v79, v74, v75
	v_cvt_pk_bf16_f32 v68, v68, v69
	v_cvt_pk_bf16_f32 v69, v70, v71
	v_cvt_pk_bf16_f32 v70, v64, v65
	v_cvt_pk_bf16_f32 v71, v66, v67
	v_cvt_pk_bf16_f32 v60, v60, v61
	v_cvt_pk_bf16_f32 v61, v62, v63
	v_cvt_pk_bf16_f32 v62, v56, v57
	v_cvt_pk_bf16_f32 v63, v58, v59
	v_cvt_pk_bf16_f32 v52, v52, v53
	v_cvt_pk_bf16_f32 v53, v54, v55
	v_cvt_pk_bf16_f32 v54, v48, v49
	v_cvt_pk_bf16_f32 v55, v50, v51
	v_cvt_pk_bf16_f32 v44, v44, v45
	v_cvt_pk_bf16_f32 v45, v46, v47
	v_cvt_pk_bf16_f32 v46, v40, v41
	v_cvt_pk_bf16_f32 v47, v42, v43
	v_cvt_pk_bf16_f32 v36, v36, v37
	v_cvt_pk_bf16_f32 v37, v38, v39
	v_cvt_pk_bf16_f32 v38, v32, v33
	v_cvt_pk_bf16_f32 v39, v34, v35
	v_cvt_pk_bf16_f32 v28, v28, v29
	v_cvt_pk_bf16_f32 v29, v30, v31
	v_cvt_pk_bf16_f32 v30, v24, v25
	v_cvt_pk_bf16_f32 v31, v26, v27
	v_cvt_pk_bf16_f32 v20, v20, v21
	v_cvt_pk_bf16_f32 v21, v22, v23
	v_cvt_pk_bf16_f32 v22, v16, v17
	v_cvt_pk_bf16_f32 v23, v18, v19
	v_cvt_pk_bf16_f32 v12, v12, v13
	v_cvt_pk_bf16_f32 v13, v14, v15
	v_cvt_pk_bf16_f32 v14, v8, v9
	v_cvt_pk_bf16_f32 v15, v10, v11
	v_cvt_pk_bf16_f32 v4, v4, v5
	v_cvt_pk_bf16_f32 v5, v6, v7
	v_cvt_pk_bf16_f32 v6, v0, v1
	v_cvt_pk_bf16_f32 v7, v2, v3
	v_lshrrev_b32_e32 v160, 8, v208
	v_and_b32_e32 v161, 15, v208
	v_lshl_add_u32 v160, v160, 6, v161
	v_bfe_u32 v161, v208, 6, 2
	v_bfe_u32 v162, v208, 4, 2
	v_lshlrev_b32_e32 v161, 6, v161
	v_lshl_add_u32 v161, v162, 4, v161
	v_lshl_add_u32 v138, v160, 9, v161
	s_waitcnt lgkmcnt(0)
	s_add_u32 s98, s60, 0x74c2800
	s_addc_u32 s99, s61, 0
	s_add_u32 s98, s98, s18
	s_addc_u32 s99, s99, s19
	s_add_u32 s78, s98, 0x0
	s_addc_u32 s79, s99, 0
	global_store_dwordx4 v138, v[124:127], s[78:79] nt
	s_add_u32 s78, s98, 0x0
	s_addc_u32 s79, s99, 0
	global_store_dwordx4 v138, v[120:123], s[78:79] offset:256 nt
	s_add_u32 s78, s98, 0x2000
	s_addc_u32 s79, s99, 0
	global_store_dwordx4 v138, v[112:115], s[78:79] nt
	s_add_u32 s78, s98, 0x2000
	s_addc_u32 s79, s99, 0
	global_store_dwordx4 v138, v[104:107], s[78:79] offset:256 nt
	s_add_u32 s78, s98, 0x4000
	s_addc_u32 s79, s99, 0
	global_store_dwordx4 v138, v[96:99], s[78:79] nt
	s_add_u32 s78, s98, 0x4000
	s_addc_u32 s79, s99, 0
	global_store_dwordx4 v138, v[88:91], s[78:79] offset:256 nt
	s_add_u32 s78, s98, 0x6000
	s_addc_u32 s79, s99, 0
	global_store_dwordx4 v138, v[76:79], s[78:79] nt
	s_add_u32 s78, s98, 0x6000
	s_addc_u32 s79, s99, 0
	global_store_dwordx4 v138, v[68:71], s[78:79] offset:256 nt
	s_add_u32 s78, s98, 0x10000
	s_addc_u32 s79, s99, 0
	global_store_dwordx4 v138, v[60:63], s[78:79] nt
	s_add_u32 s78, s98, 0x10000
	s_addc_u32 s79, s99, 0
	global_store_dwordx4 v138, v[52:55], s[78:79] offset:256 nt
	s_add_u32 s78, s98, 0x12000
	s_addc_u32 s79, s99, 0
	global_store_dwordx4 v138, v[44:47], s[78:79] nt
	s_add_u32 s78, s98, 0x12000
	s_addc_u32 s79, s99, 0
	global_store_dwordx4 v138, v[36:39], s[78:79] offset:256 nt
	s_add_u32 s78, s98, 0x14000
	s_addc_u32 s79, s99, 0
	global_store_dwordx4 v138, v[28:31], s[78:79] nt
	s_add_u32 s78, s98, 0x14000
	s_addc_u32 s79, s99, 0
	global_store_dwordx4 v138, v[20:23], s[78:79] offset:256 nt
	s_add_u32 s78, s98, 0x16000
	s_addc_u32 s79, s99, 0
	global_store_dwordx4 v138, v[12:15], s[78:79] nt
	s_add_u32 s78, s98, 0x16000
	s_addc_u32 s79, s99, 0
	global_store_dwordx4 v138, v[4:7], s[78:79] offset:256 nt
	s_branch .LBB0_225

.Lp2_next:
	s_load_dwordx2 s[60:61], s[62:63], 0xc0
	s_mul_i32 s18, s43, 49
	s_add_i32 s18, s18, s42
	s_ashr_i32 s19, s18, 31
	s_lshl_b64 s[18:19], s[18:19], 17
	v_cvt_pk_bf16_f32 v124, v124, v125
	v_cvt_pk_bf16_f32 v125, v126, v127
	v_cvt_pk_bf16_f32 v126, v128, v129
	v_cvt_pk_bf16_f32 v127, v130, v131
	v_cvt_pk_bf16_f32 v120, v120, v121
	v_cvt_pk_bf16_f32 v121, v122, v123
	v_cvt_pk_bf16_f32 v122, v116, v117
	v_cvt_pk_bf16_f32 v123, v118, v119
	v_cvt_pk_bf16_f32 v112, v112, v113
	v_cvt_pk_bf16_f32 v113, v114, v115
	v_cvt_pk_bf16_f32 v114, v108, v109
	v_cvt_pk_bf16_f32 v115, v110, v111
	v_cvt_pk_bf16_f32 v104, v104, v105
	v_cvt_pk_bf16_f32 v105, v106, v107
	v_cvt_pk_bf16_f32 v106, v100, v101
	v_cvt_pk_bf16_f32 v107, v102, v103
	v_cvt_pk_bf16_f32 v96, v96, v97
	v_cvt_pk_bf16_f32 v97, v98, v99
	v_cvt_pk_bf16_f32 v98, v92, v93
	v_cvt_pk_bf16_f32 v99, v94, v95
	v_cvt_pk_bf16_f32 v88, v88, v89
	v_cvt_pk_bf16_f32 v89, v90, v91
	v_cvt_pk_bf16_f32 v90, v84, v85
	v_cvt_pk_bf16_f32 v91, v86, v87
	v_cvt_pk_bf16_f32 v76, v76, v77
	v_cvt_pk_bf16_f32 v77, v78, v79
	v_cvt_pk_bf16_f32 v78, v72, v73
	v_cvt_pk_bf16_f32 v79, v74, v75
	v_cvt_pk_bf16_f32 v140, v68, v69
	v_cvt_pk_bf16_f32 v141, v70, v71
	v_cvt_pk_bf16_f32 v142, v64, v65
	v_cvt_pk_bf16_f32 v143, v66, v67
	v_cvt_pk_bf16_f32 v60, v60, v61
	v_cvt_pk_bf16_f32 v61, v62, v63
	v_cvt_pk_bf16_f32 v62, v56, v57
	v_cvt_pk_bf16_f32 v63, v58, v59
	v_cvt_pk_bf16_f32 v52, v52, v53
	v_cvt_pk_bf16_f32 v53, v54, v55
	v_cvt_pk_bf16_f32 v54, v48, v49
	v_cvt_pk_bf16_f32 v55, v50, v51
	v_cvt_pk_bf16_f32 v44, v44, v45
	v_cvt_pk_bf16_f32 v45, v46, v47
	v_cvt_pk_bf16_f32 v46, v40, v41
	v_cvt_pk_bf16_f32 v47, v42, v43
	v_cvt_pk_bf16_f32 v36, v36, v37
	v_cvt_pk_bf16_f32 v37, v38, v39
	v_cvt_pk_bf16_f32 v38, v32, v33
	v_cvt_pk_bf16_f32 v39, v34, v35
	v_cvt_pk_bf16_f32 v28, v28, v29
	v_cvt_pk_bf16_f32 v29, v30, v31
	v_cvt_pk_bf16_f32 v30, v24, v25
	v_cvt_pk_bf16_f32 v31, v26, v27
	v_cvt_pk_bf16_f32 v20, v20, v21
	v_cvt_pk_bf16_f32 v21, v22, v23
	v_cvt_pk_bf16_f32 v22, v16, v17
	v_cvt_pk_bf16_f32 v23, v18, v19
	v_cvt_pk_bf16_f32 v144, v12, v13
	v_cvt_pk_bf16_f32 v145, v14, v15
	v_cvt_pk_bf16_f32 v146, v8, v9
	v_cvt_pk_bf16_f32 v147, v10, v11
	v_cvt_pk_bf16_f32 v148, v4, v5
	v_cvt_pk_bf16_f32 v149, v6, v7
	v_cvt_pk_bf16_f32 v150, v0, v1
	v_cvt_pk_bf16_f32 v151, v2, v3
	v_lshrrev_b32_e32 v160, 8, v208
	v_and_b32_e32 v161, 15, v208
	v_lshl_add_u32 v160, v160, 6, v161
	v_bfe_u32 v161, v208, 6, 2
	v_bfe_u32 v162, v208, 4, 2
	v_lshlrev_b32_e32 v161, 6, v161
	v_lshl_add_u32 v161, v162, 4, v161
	v_lshl_add_u32 v138, v160, 9, v161
	s_waitcnt lgkmcnt(0)
	s_add_u32 s98, s60, 0x74c2800
	s_addc_u32 s99, s61, 0
	s_add_u32 s98, s98, s18
	s_addc_u32 s99, s99, s19
	s_mov_b32 s42, s40
	s_mov_b32 s43, s41
	s_mov_b64 s[20:21], s[8:9]
	s_mov_b64 s[18:19], s[10:11]
	s_add_u32 s22, s20, 0x80
	s_addc_u32 s23, s21, 0
	v_lshl_add_u64 v[164:165], s[22:23], 0, v[156:157]
	s_add_i32 m0, s29, 0xc000
	s_nop 0
	global_load_lds_dwordx4 v[164:165], off
	v_lshl_add_u64 v[164:165], s[22:23], 0, v[154:155]
	s_add_i32 m0, s29, 0xe000
	s_nop 0
	global_load_lds_dwordx4 v[164:165], off
	s_add_u32 s78, s98, 0x0
	s_addc_u32 s79, s99, 0
	global_store_dwordx4 v138, v[124:127], s[78:79] nt
	s_add_u32 s78, s98, 0x2000
	s_addc_u32 s79, s99, 0
	global_store_dwordx4 v138, v[112:115], s[78:79] nt
	s_add_u32 s78, s98, 0x4000
	s_addc_u32 s79, s99, 0
	global_store_dwordx4 v138, v[96:99], s[78:79] nt
	s_add_u32 s78, s98, 0x6000
	s_addc_u32 s79, s99, 0
	global_store_dwordx4 v138, v[76:79], s[78:79] nt
	s_add_u32 s78, s98, 0x0
	s_addc_u32 s79, s99, 0
	global_store_dwordx4 v138, v[120:123], s[78:79] offset:256 nt
	s_add_u32 s78, s98, 0x2000
	s_addc_u32 s79, s99, 0
	global_store_dwordx4 v138, v[104:107], s[78:79] offset:256 nt
	s_add_u32 s78, s98, 0x10000
	s_addc_u32 s79, s99, 0
	global_store_dwordx4 v138, v[60:63], s[78:79] nt
	s_add_u32 s78, s98, 0x12000
	s_addc_u32 s79, s99, 0
	global_store_dwordx4 v138, v[44:47], s[78:79] nt
	s_add_u32 s78, s98, 0x10000
	s_addc_u32 s79, s99, 0
	global_store_dwordx4 v138, v[52:55], s[78:79] offset:256 nt
	s_add_u32 s78, s98, 0x12000
	s_addc_u32 s79, s99, 0
	global_store_dwordx4 v138, v[36:39], s[78:79] offset:256 nt
	s_add_i32 s39, s39, 1
	s_mul_i32 s6, s3, s39
	s_mul_hi_u32 s7, s2, s39
	s_add_i32 s7, s7, s6
	s_mul_i32 s6, s2, s39
	s_add_u32 s10, s6, s64
	s_addc_u32 s11, s7, s65
	v_mov_b64_e32 v[160:161], 0xc40
	v_cmp_lt_i64_e64 s[8:9], s[10:11], v[160:161]
	v_mov_b64_e32 v[160:161], 0xc3f
	v_cmp_gt_i64_e64 s[6:7], s[10:11], v[160:161]
	s_and_b64 vcc, exec, s[6:7]
	s_cbranch_vccnz .Lp2_u217
	s_ashr_i32 s11, s10, 31
	s_lshr_b32 s11, s11, 29
	s_add_i32 s11, s10, s11
	s_ashr_i32 s22, s11, 3
	s_and_b32 s11, s11, -8
	s_sub_i32 s10, s10, s11
	s_cmp_lt_i32 s10, 0
	s_cselect_b32 s11, s69, 0x188
	s_mul_i32 s10, s10, s11
	s_add_i32 s10, s10, s22
	s_mul_hi_i32 s11, s10, 0x5397829d
	s_lshr_b32 s22, s11, 31
	s_ashr_i32 s11, s11, 6
	s_add_i32 s11, s11, s22
	s_lshl_b32 s22, s11, 2
	s_sub_i32 s23, 64, s22
	s_min_i32 s23, s23, 4
	s_abs_i32 s40, s23
	v_cvt_f32_u32_e32 v160, s40
	s_sub_i32 s44, 0, s40
	s_mulk_i32 s11, 0xc4
	s_sub_i32 s10, s10, s11
	v_rcp_iflag_f32_e32 v160, v160
	s_abs_i32 s11, s10
	s_xor_b32 s41, s10, s23
	s_ashr_i32 s41, s41, 31
	v_mul_f32_e32 v160, 0x4f7ffffe, v160
	v_cvt_u32_f32_e32 v160, v160
	s_nop 0
	v_readfirstlane_b32 s45, v160
	s_mul_i32 s44, s44, s45
	s_mul_hi_u32 s44, s45, s44
	s_add_i32 s45, s45, s44
	s_mul_hi_u32 s44, s11, s45
	s_mul_i32 s45, s44, s40
	s_sub_i32 s11, s11, s45
	s_add_i32 s46, s44, 1
	s_sub_i32 s45, s11, s40
	s_cmp_ge_u32 s11, s40
	s_cselect_b32 s44, s46, s44
	s_cselect_b32 s11, s45, s11
	s_add_i32 s45, s44, 1
	s_cmp_ge_u32 s11, s40
	s_cselect_b32 s11, s45, s44
	s_xor_b32 s11, s11, s41
	s_sub_i32 s40, s11, s41
	s_mul_i32 s11, s40, s23
	s_sub_i32 s10, s10, s11
	s_add_i32 s41, s22, s10
.Lp2_u217:
	v_cndmask_b32_e64 v160, 0, 1, s[8:9]
	v_cmp_ne_u32_e64 s[10:11], 1, v160
	s_andn2_b64 vcc, exec, s[8:9]
	s_mov_b64 s[8:9], s[20:21]
	s_cbranch_vccnz .Lp2_u219
	s_ashr_i32 s8, s41, 31
	s_mul_hi_u32 s9, s14, s41
	s_mul_i32 s8, s14, s8
	s_add_i32 s8, s9, s8
	s_mul_i32 s9, s15, s41
	s_add_i32 s9, s8, s9
	s_mul_i32 s8, s14, s41
	s_add_u32 s8, s24, s8
	s_addc_u32 s9, s5, s9

.Lp2_u221:
	s_add_u32 s44, s18, 0x100
	s_addc_u32 s45, s19, 0
	s_add_u32 s18, s20, 0x80
	s_addc_u32 s19, s21, 0
	s_mov_b32 s20, 0
	s_add_i32 s46, s20, 2
	s_add_u32 s22, s18, 0x80
	s_addc_u32 s21, s19, 0
	s_add_i32 s47, 0, 0x10000
	v_add_u32_e32 v164, s47, v158
	ds_read_b128 v[160:163], v164
	ds_read_b128 v[176:179], v164 offset:1024
	ds_read_b128 v[180:183], v164 offset:2048
	ds_read_b128 v[184:187], v164 offset:3072
	s_cmp_eq_u32 s38, s20
	s_cselect_b32 s20, s8, s22
	s_cselect_b32 s21, s9, s21
	s_cselect_b32 s23, s11, s45
	s_cselect_b32 s22, s10, s44
	ds_read_b128 v[188:191], v159
	ds_read_b128 v[192:195], v159 offset:1024
	ds_read_b128 v[196:199], v159 offset:2048
	ds_read_b128 v[200:203], v159 offset:3072
	ds_read_b128 v[204:207], v159 offset:4096
	ds_read_b128 v[218:221], v159 offset:5120
	ds_read_b128 v[224:227], v159 offset:6144
	ds_read_b128 v[228:231], v159 offset:7168
	s_add_u32 s78, s98, 0x4000
	s_addc_u32 s79, s99, 0
	global_store_dwordx4 v138, v[88:91], s[78:79] offset:256 nt
	s_waitcnt lgkmcnt(8)
	s_barrier
	s_waitcnt lgkmcnt(0)
	s_setprio 1
	s_waitcnt lgkmcnt(0)
	v_mfma_f32_16x16x32_bf16 v[124:127], v[160:163], v[188:191], 0
	v_mfma_f32_16x16x32_bf16 v[128:131], v[180:183], v[188:191], 0
	v_mfma_f32_16x16x32_bf16 v[112:115], v[160:163], v[196:199], 0
	v_mfma_f32_16x16x32_bf16 v[108:111], v[180:183], v[196:199], 0
	v_mfma_f32_16x16x32_bf16 v[96:99], v[160:163], v[204:207], 0
	v_mfma_f32_16x16x32_bf16 v[92:95], v[180:183], v[204:207], 0
	v_mfma_f32_16x16x32_bf16 v[76:79], v[160:163], v[224:227], 0
	v_mfma_f32_16x16x32_bf16 v[72:75], v[180:183], v[224:227], 0
	v_mfma_f32_16x16x32_bf16 v[124:127], v[176:179], v[192:195], v[124:127]
	v_mfma_f32_16x16x32_bf16 v[128:131], v[184:187], v[192:195], v[128:131]
	v_mfma_f32_16x16x32_bf16 v[112:115], v[176:179], v[200:203], v[112:115]
	v_mfma_f32_16x16x32_bf16 v[108:111], v[184:187], v[200:203], v[108:111]
	v_mfma_f32_16x16x32_bf16 v[96:99], v[176:179], v[218:221], v[96:99]
	v_mfma_f32_16x16x32_bf16 v[92:95], v[184:187], v[218:221], v[92:95]
	v_mfma_f32_16x16x32_bf16 v[76:79], v[176:179], v[228:231], v[76:79]
	v_mfma_f32_16x16x32_bf16 v[72:75], v[184:187], v[228:231], v[72:75]
	s_setprio 0
	s_barrier
	s_add_i32 s48, 0, 0x14000
	v_add_u32_e32 v164, s48, v158
	s_add_i32 s47, s47, s28
	ds_read_b128 v[232:235], v164
	ds_read_b128 v[236:239], v164 offset:1024
	ds_read_b128 v[240:243], v164 offset:2048
	ds_read_b128 v[244:247], v164 offset:3072
	v_lshl_add_u64 v[164:165], s[22:23], 0, v[166:167]
	s_mov_b32 m0, s47
	v_lshl_add_u64 v[248:249], s[22:23], 0, v[132:133]
	global_load_lds_dwordx4 v[164:165], off
	s_add_i32 m0, s47, 0x2000
	s_nop 0
	global_load_lds_dwordx4 v[248:249], off
	s_add_u32 s78, s98, 0x14000
	s_addc_u32 s79, s99, 0
	global_store_dwordx4 v138, v[28:31], s[78:79] nt
	s_barrier
	s_waitcnt lgkmcnt(0)
	s_setprio 1
	s_waitcnt lgkmcnt(0)
	v_mfma_f32_16x16x32_bf16 v[120:123], v[232:235], v[188:191], 0
	v_mfma_f32_16x16x32_bf16 v[116:119], v[240:243], v[188:191], 0
	v_mfma_f32_16x16x32_bf16 v[104:107], v[232:235], v[196:199], 0
	v_mfma_f32_16x16x32_bf16 v[100:103], v[240:243], v[196:199], 0
	v_mfma_f32_16x16x32_bf16 v[88:91], v[232:235], v[204:207], 0
	v_mfma_f32_16x16x32_bf16 v[84:87], v[240:243], v[204:207], 0
	v_mfma_f32_16x16x32_bf16 v[68:71], v[232:235], v[224:227], 0
	v_mfma_f32_16x16x32_bf16 v[64:67], v[240:243], v[224:227], 0
	v_mfma_f32_16x16x32_bf16 v[120:123], v[236:239], v[192:195], v[120:123]
	v_mfma_f32_16x16x32_bf16 v[116:119], v[244:247], v[192:195], v[116:119]
	v_mfma_f32_16x16x32_bf16 v[104:107], v[236:239], v[200:203], v[104:107]
	v_mfma_f32_16x16x32_bf16 v[100:103], v[244:247], v[200:203], v[100:103]
	v_mfma_f32_16x16x32_bf16 v[88:91], v[236:239], v[218:221], v[88:91]
	v_mfma_f32_16x16x32_bf16 v[84:87], v[244:247], v[218:221], v[84:87]
	v_mfma_f32_16x16x32_bf16 v[68:71], v[236:239], v[228:231], v[68:71]
	v_mfma_f32_16x16x32_bf16 v[64:67], v[244:247], v[228:231], v[64:67]
	s_setprio 0
	s_mov_b32 m0, s29
	v_lshl_add_u64 v[250:251], s[20:21], 0, v[136:137]
	s_barrier
	ds_read_b128 v[188:191], v159 offset:16384
	ds_read_b128 v[192:195], v159 offset:17408
	ds_read_b128 v[196:199], v159 offset:18432
	ds_read_b128 v[200:203], v159 offset:19456
	ds_read_b128 v[204:207], v159 offset:20480
	ds_read_b128 v[218:221], v159 offset:21504
	ds_read_b128 v[224:227], v159 offset:22528
	ds_read_b128 v[228:231], v159 offset:23552
	global_load_lds_dwordx4 v[250:251], off
	v_lshl_add_u64 v[210:211], s[20:21], 0, v[134:135]
	s_mov_b32 m0, s30
	s_nop 0
	global_load_lds_dwordx4 v[210:211], off
	s_add_u32 s78, s98, 0x14000
	s_addc_u32 s79, s99, 0
	global_store_dwordx4 v138, v[20:23], s[78:79] offset:256 nt
	s_barrier
	s_waitcnt lgkmcnt(0)
	s_setprio 1
	s_waitcnt lgkmcnt(0)
	v_mfma_f32_16x16x32_bf16 v[60:63], v[160:163], v[188:191], 0
	v_mfma_f32_16x16x32_bf16 v[56:59], v[180:183], v[188:191], 0
	v_mfma_f32_16x16x32_bf16 v[44:47], v[160:163], v[196:199], 0
	v_mfma_f32_16x16x32_bf16 v[40:43], v[180:183], v[196:199], 0
	v_mfma_f32_16x16x32_bf16 v[28:31], v[160:163], v[204:207], 0
	v_mfma_f32_16x16x32_bf16 v[24:27], v[180:183], v[204:207], 0
	v_mfma_f32_16x16x32_bf16 v[12:15], v[160:163], v[224:227], 0
	v_mfma_f32_16x16x32_bf16 v[8:11], v[180:183], v[224:227], 0
	v_mfma_f32_16x16x32_bf16 v[60:63], v[176:179], v[192:195], v[60:63]
	v_mfma_f32_16x16x32_bf16 v[56:59], v[184:187], v[192:195], v[56:59]
	v_mfma_f32_16x16x32_bf16 v[44:47], v[176:179], v[200:203], v[44:47]
	v_mfma_f32_16x16x32_bf16 v[40:43], v[184:187], v[200:203], v[40:43]
	v_mfma_f32_16x16x32_bf16 v[28:31], v[176:179], v[218:221], v[28:31]
	v_mfma_f32_16x16x32_bf16 v[24:27], v[184:187], v[218:221], v[24:27]
	v_mfma_f32_16x16x32_bf16 v[12:15], v[176:179], v[228:231], v[12:15]
	v_mfma_f32_16x16x32_bf16 v[8:11], v[184:187], v[228:231], v[8:11]
	s_setprio 0
	s_barrier
	s_add_u32 s22, s22, s12
	s_addc_u32 s23, s23, s13
	s_add_i32 s47, s48, s28
	v_lshl_add_u64 v[170:171], s[22:23], 0, v[166:167]
	s_mov_b32 m0, s47
	v_lshl_add_u64 v[172:173], s[22:23], 0, v[132:133]
	global_load_lds_dwordx4 v[170:171], off
	s_add_i32 m0, s47, 0x2000
	s_nop 0
	global_load_lds_dwordx4 v[172:173], off
	s_waitcnt vmcnt(19)
	s_barrier
	s_setprio 1
	v_mfma_f32_16x16x32_bf16 v[52:55], v[232:235], v[188:191], 0
	v_mfma_f32_16x16x32_bf16 v[48:51], v[240:243], v[188:191], 0
	v_mfma_f32_16x16x32_bf16 v[36:39], v[232:235], v[196:199], 0
	v_mfma_f32_16x16x32_bf16 v[32:35], v[240:243], v[196:199], 0
	v_mfma_f32_16x16x32_bf16 v[20:23], v[232:235], v[204:207], 0
	v_mfma_f32_16x16x32_bf16 v[16:19], v[240:243], v[204:207], 0
	v_mfma_f32_16x16x32_bf16 v[4:7], v[232:235], v[224:227], 0
	v_mfma_f32_16x16x32_bf16 v[0:3], v[240:243], v[224:227], 0
	v_mfma_f32_16x16x32_bf16 v[52:55], v[236:239], v[192:195], v[52:55]
	v_mfma_f32_16x16x32_bf16 v[48:51], v[244:247], v[192:195], v[48:51]
	v_mfma_f32_16x16x32_bf16 v[36:39], v[236:239], v[200:203], v[36:39]
	v_mfma_f32_16x16x32_bf16 v[32:35], v[244:247], v[200:203], v[32:35]
	v_mfma_f32_16x16x32_bf16 v[20:23], v[236:239], v[218:221], v[20:23]
	v_mfma_f32_16x16x32_bf16 v[16:19], v[244:247], v[218:221], v[16:19]
	v_mfma_f32_16x16x32_bf16 v[4:7], v[236:239], v[228:231], v[4:7]
	v_mfma_f32_16x16x32_bf16 v[0:3], v[244:247], v[228:231], v[0:3]
	s_setprio 0
	s_add_i32 s22, 0, 0x18000
	v_add_u32_e32 v169, s22, v158
	s_barrier
	ds_read_b128 v[160:163], v169
	ds_read_b128 v[176:179], v169 offset:1024
	ds_read_b128 v[180:183], v169 offset:2048
	ds_read_b128 v[184:187], v169 offset:3072
	s_add_u32 s20, s20, s12
	s_addc_u32 s21, s21, s13
	s_mov_b32 m0, s31
	v_lshl_add_u64 v[232:233], s[20:21], 0, v[136:137]
	ds_read_b128 v[188:191], v159 offset:32768
	ds_read_b128 v[192:195], v159 offset:33792
	ds_read_b128 v[196:199], v159 offset:34816
	ds_read_b128 v[200:203], v159 offset:35840
	ds_read_b128 v[204:207], v159 offset:36864
	ds_read_b128 v[218:221], v159 offset:37888
	ds_read_b128 v[224:227], v159 offset:38912
	ds_read_b128 v[228:231], v159 offset:39936
	global_load_lds_dwordx4 v[232:233], off
	v_lshl_add_u64 v[232:233], s[20:21], 0, v[134:135]
	s_mov_b32 m0, s34
	s_nop 0
	global_load_lds_dwordx4 v[232:233], off
	s_add_u32 s78, s98, 0x6000
	s_addc_u32 s79, s99, 0
	global_store_dwordx4 v138, v[140:143], s[78:79] offset:256 nt
	s_waitcnt lgkmcnt(8)
	s_barrier
	s_waitcnt lgkmcnt(0)
	s_setprio 1
	s_waitcnt lgkmcnt(0)
	v_mfma_f32_16x16x32_bf16 v[124:127], v[160:163], v[188:191], v[124:127]
	v_mfma_f32_16x16x32_bf16 v[128:131], v[180:183], v[188:191], v[128:131]
	v_mfma_f32_16x16x32_bf16 v[112:115], v[160:163], v[196:199], v[112:115]
	v_mfma_f32_16x16x32_bf16 v[108:111], v[180:183], v[196:199], v[108:111]
	v_mfma_f32_16x16x32_bf16 v[96:99], v[160:163], v[204:207], v[96:99]
	v_mfma_f32_16x16x32_bf16 v[92:95], v[180:183], v[204:207], v[92:95]
	v_mfma_f32_16x16x32_bf16 v[76:79], v[160:163], v[224:227], v[76:79]
	v_mfma_f32_16x16x32_bf16 v[72:75], v[180:183], v[224:227], v[72:75]
	v_mfma_f32_16x16x32_bf16 v[124:127], v[176:179], v[192:195], v[124:127]
	v_mfma_f32_16x16x32_bf16 v[128:131], v[184:187], v[192:195], v[128:131]
	v_mfma_f32_16x16x32_bf16 v[112:115], v[176:179], v[200:203], v[112:115]
	v_mfma_f32_16x16x32_bf16 v[108:111], v[184:187], v[200:203], v[108:111]
	v_mfma_f32_16x16x32_bf16 v[96:99], v[176:179], v[218:221], v[96:99]
	v_mfma_f32_16x16x32_bf16 v[92:95], v[184:187], v[218:221], v[92:95]
	v_mfma_f32_16x16x32_bf16 v[76:79], v[176:179], v[228:231], v[76:79]
	v_mfma_f32_16x16x32_bf16 v[72:75], v[184:187], v[228:231], v[72:75]
	s_setprio 0
	s_barrier
	s_add_i32 s20, 0, 0x1c000
	s_add_i32 s21, s22, s28
	v_add_u32_e32 v169, s20, v158
	v_lshl_add_u64 v[164:165], v[164:165], 0, s[88:89]
	s_mov_b32 m0, s21
	ds_read_b128 v[232:235], v169
	ds_read_b128 v[236:239], v169 offset:1024
	ds_read_b128 v[240:243], v169 offset:2048
	ds_read_b128 v[244:247], v169 offset:3072
	global_load_lds_dwordx4 v[164:165], off
	v_lshl_add_u64 v[164:165], v[248:249], 0, s[88:89]
	s_add_i32 m0, s21, 0x2000
	s_nop 0
	global_load_lds_dwordx4 v[164:165], off
	s_add_u32 s78, s98, 0x16000
	s_addc_u32 s79, s99, 0
	global_store_dwordx4 v138, v[144:147], s[78:79] nt
	s_barrier
	s_waitcnt lgkmcnt(0)
	s_setprio 1
	s_waitcnt lgkmcnt(0)
	v_mfma_f32_16x16x32_bf16 v[120:123], v[232:235], v[188:191], v[120:123]
	v_mfma_f32_16x16x32_bf16 v[116:119], v[240:243], v[188:191], v[116:119]
	v_mfma_f32_16x16x32_bf16 v[104:107], v[232:235], v[196:199], v[104:107]
	v_mfma_f32_16x16x32_bf16 v[100:103], v[240:243], v[196:199], v[100:103]
	v_mfma_f32_16x16x32_bf16 v[88:91], v[232:235], v[204:207], v[88:91]
	v_mfma_f32_16x16x32_bf16 v[84:87], v[240:243], v[204:207], v[84:87]
	v_mfma_f32_16x16x32_bf16 v[68:71], v[232:235], v[224:227], v[68:71]
	v_mfma_f32_16x16x32_bf16 v[64:67], v[240:243], v[224:227], v[64:67]
	v_mfma_f32_16x16x32_bf16 v[120:123], v[236:239], v[192:195], v[120:123]
	v_mfma_f32_16x16x32_bf16 v[116:119], v[244:247], v[192:195], v[116:119]
	v_mfma_f32_16x16x32_bf16 v[104:107], v[236:239], v[200:203], v[104:107]
	v_mfma_f32_16x16x32_bf16 v[100:103], v[244:247], v[200:203], v[100:103]
	v_mfma_f32_16x16x32_bf16 v[88:91], v[236:239], v[218:221], v[88:91]
	v_mfma_f32_16x16x32_bf16 v[84:87], v[244:247], v[218:221], v[84:87]
	v_mfma_f32_16x16x32_bf16 v[68:71], v[236:239], v[228:231], v[68:71]
	v_mfma_f32_16x16x32_bf16 v[64:67], v[244:247], v[228:231], v[64:67]
	s_setprio 0
	s_mov_b32 m0, s36
	v_lshl_add_u64 v[164:165], v[250:251], 0, s[88:89]
	s_barrier
	ds_read_b128 v[188:191], v159 offset:49152
	ds_read_b128 v[192:195], v159 offset:50176
	ds_read_b128 v[196:199], v159 offset:51200
	ds_read_b128 v[200:203], v159 offset:52224
	ds_read_b128 v[204:207], v159 offset:53248
	ds_read_b128 v[218:221], v159 offset:54272
	ds_read_b128 v[224:227], v159 offset:55296
	ds_read_b128 v[228:231], v159 offset:56320
	global_load_lds_dwordx4 v[164:165], off
	v_lshl_add_u64 v[164:165], v[210:211], 0, s[88:89]
	s_mov_b32 m0, s37
	s_nop 0
	global_load_lds_dwordx4 v[164:165], off
	s_add_u32 s78, s98, 0x16000
	s_addc_u32 s79, s99, 0
	global_store_dwordx4 v138, v[148:151], s[78:79] offset:256 nt
	s_barrier
	s_waitcnt lgkmcnt(0)
	s_setprio 1
	s_waitcnt lgkmcnt(0)
	v_mfma_f32_16x16x32_bf16 v[60:63], v[160:163], v[188:191], v[60:63]
	v_mfma_f32_16x16x32_bf16 v[56:59], v[180:183], v[188:191], v[56:59]
	v_mfma_f32_16x16x32_bf16 v[44:47], v[160:163], v[196:199], v[44:47]
	v_mfma_f32_16x16x32_bf16 v[40:43], v[180:183], v[196:199], v[40:43]
	v_mfma_f32_16x16x32_bf16 v[28:31], v[160:163], v[204:207], v[28:31]
	v_mfma_f32_16x16x32_bf16 v[24:27], v[180:183], v[204:207], v[24:27]
	v_mfma_f32_16x16x32_bf16 v[12:15], v[160:163], v[224:227], v[12:15]
	v_mfma_f32_16x16x32_bf16 v[8:11], v[180:183], v[224:227], v[8:11]
	v_mfma_f32_16x16x32_bf16 v[60:63], v[176:179], v[192:195], v[60:63]
	v_mfma_f32_16x16x32_bf16 v[56:59], v[184:187], v[192:195], v[56:59]
	v_mfma_f32_16x16x32_bf16 v[44:47], v[176:179], v[200:203], v[44:47]
	v_mfma_f32_16x16x32_bf16 v[40:43], v[184:187], v[200:203], v[40:43]
	v_mfma_f32_16x16x32_bf16 v[28:31], v[176:179], v[218:221], v[28:31]
	v_mfma_f32_16x16x32_bf16 v[24:27], v[184:187], v[218:221], v[24:27]
	v_mfma_f32_16x16x32_bf16 v[12:15], v[176:179], v[228:231], v[12:15]
	v_mfma_f32_16x16x32_bf16 v[8:11], v[184:187], v[228:231], v[8:11]
	s_setprio 0
	s_barrier
	s_add_i32 s20, s20, s28
	v_lshl_add_u64 v[160:161], v[170:171], 0, s[88:89]
	s_mov_b32 m0, s20
	s_nop 0
	global_load_lds_dwordx4 v[160:161], off
	v_lshl_add_u64 v[160:161], v[172:173], 0, s[88:89]
	s_add_i32 m0, s20, 0x2000
	s_nop 0
	global_load_lds_dwordx4 v[160:161], off
	s_waitcnt vmcnt(9)
	s_barrier
	s_setprio 1
	v_mfma_f32_16x16x32_bf16 v[52:55], v[232:235], v[188:191], v[52:55]
	v_mfma_f32_16x16x32_bf16 v[48:51], v[240:243], v[188:191], v[48:51]
	v_mfma_f32_16x16x32_bf16 v[36:39], v[232:235], v[196:199], v[36:39]
	v_mfma_f32_16x16x32_bf16 v[32:35], v[240:243], v[196:199], v[32:35]
	v_mfma_f32_16x16x32_bf16 v[20:23], v[232:235], v[204:207], v[20:23]
	v_mfma_f32_16x16x32_bf16 v[16:19], v[240:243], v[204:207], v[16:19]
	v_mfma_f32_16x16x32_bf16 v[4:7], v[232:235], v[224:227], v[4:7]
	v_mfma_f32_16x16x32_bf16 v[0:3], v[240:243], v[224:227], v[0:3]
	v_mfma_f32_16x16x32_bf16 v[52:55], v[236:239], v[192:195], v[52:55]
	v_mfma_f32_16x16x32_bf16 v[48:51], v[244:247], v[192:195], v[48:51]
	v_mfma_f32_16x16x32_bf16 v[36:39], v[236:239], v[200:203], v[36:39]
	v_mfma_f32_16x16x32_bf16 v[32:35], v[244:247], v[200:203], v[32:35]
	v_mfma_f32_16x16x32_bf16 v[20:23], v[236:239], v[218:221], v[20:23]
	v_mfma_f32_16x16x32_bf16 v[16:19], v[244:247], v[218:221], v[16:19]
	v_mfma_f32_16x16x32_bf16 v[4:7], v[236:239], v[228:231], v[4:7]
	v_mfma_f32_16x16x32_bf16 v[0:3], v[244:247], v[228:231], v[0:3]
	s_setprio 0
	s_add_u32 s44, s44, 0x100
	s_addc_u32 s45, s45, 0
	s_add_u32 s18, s18, 0x100
	s_addc_u32 s19, s19, 0
	s_mov_b32 s20, s46
	s_barrier
	s_branch .LBB0_223
